# in-proj epilogue stores made agent-scope write-through (sc1) to shrink the L2 write-back at the following grid barrier
# baseline (speedup 1.0000x reference)
.LBB0_189:
	s_add_u32 s1, s68, 0xfff80080
	s_addc_u32 s2, s69, -1
	s_add_i32 s3, 0, 0x10000
	v_add_u32_e32 v154, s3, v143
	ds_read_b128 v[138:141], v154
	ds_read_b128 v[146:149], v154 offset:1024
	ds_read_b128 v[150:153], v154 offset:2048
	ds_read_b128 v[154:157], v154 offset:3072
	s_cmp_eq_u32 s87, 28
	s_cselect_b32 s73, s43, s2
	s_cselect_b32 s72, s81, s1
	s_cselect_b32 s71, s41, s86
	s_cselect_b32 s70, s82, s83
	v_lshl_add_u64 v[174:175], s[68:69], 0, v[134:135]
	s_add_i32 m0, s60, 0xc000
	ds_read_b128 v[158:161], v145
	ds_read_b128 v[162:165], v145 offset:1024
	ds_read_b128 v[166:169], v145 offset:2048
	ds_read_b128 v[170:173], v145 offset:3072
	ds_read_b128 v[182:185], v145 offset:4096
	ds_read_b128 v[206:209], v145 offset:5120
	ds_read_b128 v[210:213], v145 offset:6144
	ds_read_b128 v[214:217], v145 offset:7168
	global_load_lds_dwordx4 v[174:175], off
	v_lshl_add_u64 v[174:175], s[68:69], 0, v[136:137]
	s_add_i32 m0, s60, 0xe000
	s_nop 0
	global_load_lds_dwordx4 v[174:175], off
	s_waitcnt lgkmcnt(8)
	s_barrier
	s_waitcnt lgkmcnt(0)
	s_setprio 1
	s_waitcnt lgkmcnt(0)
	v_mfma_f32_16x16x32_bf16 v[124:127], v[138:141], v[158:161], v[124:127]
	v_mfma_f32_16x16x32_bf16 v[120:123], v[150:153], v[158:161], v[120:123]
	v_mfma_f32_16x16x32_bf16 v[116:119], v[138:141], v[166:169], v[116:119]
	v_mfma_f32_16x16x32_bf16 v[108:111], v[150:153], v[166:169], v[108:111]
	v_mfma_f32_16x16x32_bf16 v[100:103], v[138:141], v[182:185], v[100:103]
	v_mfma_f32_16x16x32_bf16 v[92:95], v[150:153], v[182:185], v[92:95]
	v_mfma_f32_16x16x32_bf16 v[84:87], v[138:141], v[210:213], v[84:87]
	v_mfma_f32_16x16x32_bf16 v[76:79], v[150:153], v[210:213], v[76:79]
	v_mfma_f32_16x16x32_bf16 v[124:127], v[146:149], v[162:165], v[124:127]
	v_mfma_f32_16x16x32_bf16 v[120:123], v[154:157], v[162:165], v[120:123]
	v_mfma_f32_16x16x32_bf16 v[116:119], v[146:149], v[170:173], v[116:119]
	v_mfma_f32_16x16x32_bf16 v[108:111], v[154:157], v[170:173], v[108:111]
	v_mfma_f32_16x16x32_bf16 v[100:103], v[146:149], v[206:209], v[100:103]
	v_mfma_f32_16x16x32_bf16 v[92:95], v[154:157], v[206:209], v[92:95]
	v_mfma_f32_16x16x32_bf16 v[84:87], v[146:149], v[214:217], v[84:87]
	v_mfma_f32_16x16x32_bf16 v[76:79], v[154:157], v[214:217], v[76:79]
	s_setprio 0
	s_barrier
	s_add_i32 s1, 0, 0x14000
	v_add_u32_e32 v174, s1, v143
	s_add_i32 s2, s3, s53
	ds_read_b128 v[218:221], v174
	ds_read_b128 v[222:225], v174 offset:1024
	ds_read_b128 v[226:229], v174 offset:2048
	ds_read_b128 v[230:233], v174 offset:3072
	v_lshl_add_u64 v[174:175], s[70:71], 0, v[176:177]
	s_mov_b32 m0, s2
	v_lshl_add_u64 v[186:187], s[70:71], 0, v[128:129]
	global_load_lds_dwordx4 v[174:175], off
	s_add_i32 m0, s2, 0x2000
	s_nop 0
	global_load_lds_dwordx4 v[186:187], off
	s_barrier
	s_waitcnt lgkmcnt(0)
	s_setprio 1
	s_waitcnt lgkmcnt(0)
	v_mfma_f32_16x16x32_bf16 v[112:115], v[218:221], v[158:161], v[112:115]
	v_mfma_f32_16x16x32_bf16 v[104:107], v[226:229], v[158:161], v[104:107]
	v_mfma_f32_16x16x32_bf16 v[96:99], v[218:221], v[166:169], v[96:99]
	v_mfma_f32_16x16x32_bf16 v[88:91], v[226:229], v[166:169], v[88:91]
	v_mfma_f32_16x16x32_bf16 v[80:83], v[218:221], v[182:185], v[80:83]
	v_mfma_f32_16x16x32_bf16 v[72:75], v[226:229], v[182:185], v[72:75]
	v_mfma_f32_16x16x32_bf16 v[68:71], v[218:221], v[210:213], v[68:71]
	v_mfma_f32_16x16x32_bf16 v[64:67], v[226:229], v[210:213], v[64:67]
	v_mfma_f32_16x16x32_bf16 v[112:115], v[222:225], v[162:165], v[112:115]
	v_mfma_f32_16x16x32_bf16 v[104:107], v[230:233], v[162:165], v[104:107]
	v_mfma_f32_16x16x32_bf16 v[96:99], v[222:225], v[170:173], v[96:99]
	v_mfma_f32_16x16x32_bf16 v[88:91], v[230:233], v[170:173], v[88:91]
	v_mfma_f32_16x16x32_bf16 v[80:83], v[222:225], v[206:209], v[80:83]
	v_mfma_f32_16x16x32_bf16 v[72:75], v[230:233], v[206:209], v[72:75]
	v_mfma_f32_16x16x32_bf16 v[68:71], v[222:225], v[214:217], v[68:71]
	v_mfma_f32_16x16x32_bf16 v[64:67], v[230:233], v[214:217], v[64:67]
	s_setprio 0
	s_mov_b32 m0, s60
	v_lshl_add_u64 v[200:201], s[72:73], 0, v[132:133]
	s_barrier
	ds_read_b128 v[158:161], v145 offset:16384
	ds_read_b128 v[162:165], v145 offset:17408
	ds_read_b128 v[166:169], v145 offset:18432
	ds_read_b128 v[170:173], v145 offset:19456
	ds_read_b128 v[182:185], v145 offset:20480
	ds_read_b128 v[206:209], v145 offset:21504
	ds_read_b128 v[210:213], v145 offset:22528
	ds_read_b128 v[214:217], v145 offset:23552
	global_load_lds_dwordx4 v[200:201], off
	v_lshl_add_u64 v[202:203], s[72:73], 0, v[130:131]
	s_mov_b32 m0, s61
	s_nop 0
	global_load_lds_dwordx4 v[202:203], off
	s_barrier
	s_waitcnt lgkmcnt(0)
	s_setprio 1
	s_waitcnt lgkmcnt(0)
	v_mfma_f32_16x16x32_bf16 v[60:63], v[138:141], v[158:161], v[60:63]
	v_mfma_f32_16x16x32_bf16 v[56:59], v[150:153], v[158:161], v[56:59]
	v_mfma_f32_16x16x32_bf16 v[52:55], v[138:141], v[166:169], v[52:55]
	v_mfma_f32_16x16x32_bf16 v[44:47], v[150:153], v[166:169], v[44:47]
	v_mfma_f32_16x16x32_bf16 v[36:39], v[138:141], v[182:185], v[36:39]
	v_mfma_f32_16x16x32_bf16 v[28:31], v[150:153], v[182:185], v[28:31]
	v_mfma_f32_16x16x32_bf16 v[20:23], v[138:141], v[210:213], v[20:23]
	v_mfma_f32_16x16x32_bf16 v[12:15], v[150:153], v[210:213], v[12:15]
	v_mfma_f32_16x16x32_bf16 v[60:63], v[146:149], v[162:165], v[60:63]
	v_mfma_f32_16x16x32_bf16 v[56:59], v[154:157], v[162:165], v[56:59]
	v_mfma_f32_16x16x32_bf16 v[52:55], v[146:149], v[170:173], v[52:55]
	v_mfma_f32_16x16x32_bf16 v[44:47], v[154:157], v[170:173], v[44:47]
	v_mfma_f32_16x16x32_bf16 v[36:39], v[146:149], v[206:209], v[36:39]
	v_mfma_f32_16x16x32_bf16 v[28:31], v[154:157], v[206:209], v[28:31]
	v_mfma_f32_16x16x32_bf16 v[20:23], v[146:149], v[214:217], v[20:23]
	v_mfma_f32_16x16x32_bf16 v[12:15], v[154:157], v[214:217], v[12:15]
	s_setprio 0
	s_barrier
	s_add_u32 s2, s70, 0x80000
	s_addc_u32 s3, s71, 0
	s_add_i32 s1, s1, s53
	v_lshl_add_u64 v[138:139], s[2:3], 0, v[176:177]
	s_mov_b32 m0, s1
	s_nop 0
	global_load_lds_dwordx4 v[138:139], off
	v_lshl_add_u64 v[138:139], s[2:3], 0, v[128:129]
	s_add_i32 m0, s1, 0x2000
	s_nop 0
	global_load_lds_dwordx4 v[138:139], off
	s_waitcnt vmcnt(6)
	s_barrier
	s_setprio 1
	v_mfma_f32_16x16x32_bf16 v[48:51], v[218:221], v[158:161], v[48:51]
	v_mfma_f32_16x16x32_bf16 v[40:43], v[226:229], v[158:161], v[40:43]
	v_mfma_f32_16x16x32_bf16 v[32:35], v[218:221], v[166:169], v[32:35]
	v_mfma_f32_16x16x32_bf16 v[24:27], v[226:229], v[166:169], v[24:27]
	v_mfma_f32_16x16x32_bf16 v[16:19], v[218:221], v[182:185], v[16:19]
	v_mfma_f32_16x16x32_bf16 v[8:11], v[226:229], v[182:185], v[8:11]
	v_mfma_f32_16x16x32_bf16 v[4:7], v[218:221], v[210:213], v[4:7]
	v_mfma_f32_16x16x32_bf16 v[0:3], v[226:229], v[210:213], v[0:3]
	v_mfma_f32_16x16x32_bf16 v[48:51], v[222:225], v[162:165], v[48:51]
	v_mfma_f32_16x16x32_bf16 v[40:43], v[230:233], v[162:165], v[40:43]
	v_mfma_f32_16x16x32_bf16 v[32:35], v[222:225], v[170:173], v[32:35]
	v_mfma_f32_16x16x32_bf16 v[24:27], v[230:233], v[170:173], v[24:27]
	v_mfma_f32_16x16x32_bf16 v[16:19], v[222:225], v[206:209], v[16:19]
	v_mfma_f32_16x16x32_bf16 v[8:11], v[230:233], v[206:209], v[8:11]
	v_mfma_f32_16x16x32_bf16 v[4:7], v[222:225], v[214:217], v[4:7]
	v_mfma_f32_16x16x32_bf16 v[0:3], v[230:233], v[214:217], v[0:3]
	s_setprio 0
	s_add_i32 s1, 0, 0x18000
	v_add_u32_e32 v154, s1, v143
	s_barrier
	ds_read_b128 v[138:141], v154
	ds_read_b128 v[146:149], v154 offset:1024
	ds_read_b128 v[150:153], v154 offset:2048
	ds_read_b128 v[154:157], v154 offset:3072
	s_add_u32 s2, s72, 0x80000
	s_addc_u32 s3, s73, 0
	s_mov_b32 m0, s74
	v_lshl_add_u64 v[204:205], s[2:3], 0, v[132:133]
	ds_read_b128 v[158:161], v145 offset:32768
	ds_read_b128 v[162:165], v145 offset:33792
	ds_read_b128 v[166:169], v145 offset:34816
	ds_read_b128 v[170:173], v145 offset:35840
	ds_read_b128 v[182:185], v145 offset:36864
	ds_read_b128 v[206:209], v145 offset:37888
	ds_read_b128 v[210:213], v145 offset:38912
	ds_read_b128 v[214:217], v145 offset:39936
	global_load_lds_dwordx4 v[204:205], off
	v_lshl_add_u64 v[204:205], s[2:3], 0, v[130:131]
	s_mov_b32 m0, s75
	s_nop 0
	global_load_lds_dwordx4 v[204:205], off
	s_waitcnt lgkmcnt(8)
	s_barrier
	s_waitcnt lgkmcnt(0)
	s_setprio 1
	s_waitcnt lgkmcnt(0)
	v_mfma_f32_16x16x32_bf16 v[124:127], v[138:141], v[158:161], v[124:127]
	v_mfma_f32_16x16x32_bf16 v[120:123], v[150:153], v[158:161], v[120:123]
	v_mfma_f32_16x16x32_bf16 v[116:119], v[138:141], v[166:169], v[116:119]
	v_mfma_f32_16x16x32_bf16 v[108:111], v[150:153], v[166:169], v[108:111]
	v_mfma_f32_16x16x32_bf16 v[100:103], v[138:141], v[182:185], v[100:103]
	v_mfma_f32_16x16x32_bf16 v[92:95], v[150:153], v[182:185], v[92:95]
	v_mfma_f32_16x16x32_bf16 v[84:87], v[138:141], v[210:213], v[84:87]
	v_mfma_f32_16x16x32_bf16 v[76:79], v[150:153], v[210:213], v[76:79]
	v_mfma_f32_16x16x32_bf16 v[124:127], v[146:149], v[162:165], v[124:127]
	v_mfma_f32_16x16x32_bf16 v[120:123], v[154:157], v[162:165], v[120:123]
	v_mfma_f32_16x16x32_bf16 v[116:119], v[146:149], v[170:173], v[116:119]
	v_mfma_f32_16x16x32_bf16 v[108:111], v[154:157], v[170:173], v[108:111]
	v_mfma_f32_16x16x32_bf16 v[100:103], v[146:149], v[206:209], v[100:103]
	v_mfma_f32_16x16x32_bf16 v[92:95], v[154:157], v[206:209], v[92:95]
	v_mfma_f32_16x16x32_bf16 v[84:87], v[146:149], v[214:217], v[84:87]
	v_mfma_f32_16x16x32_bf16 v[76:79], v[154:157], v[214:217], v[76:79]
	s_setprio 0
	s_barrier
	s_add_i32 s12, 0, 0x1c000
	s_add_i32 s1, s1, s53
	v_add_u32_e32 v188, s12, v143
	v_lshl_add_u64 v[174:175], v[174:175], 0, s[20:21]
	s_mov_b32 m0, s1
	ds_read_b128 v[218:221], v188
	ds_read_b128 v[222:225], v188 offset:1024
	ds_read_b128 v[226:229], v188 offset:2048
	ds_read_b128 v[230:233], v188 offset:3072
	global_load_lds_dwordx4 v[174:175], off
	v_lshl_add_u64 v[174:175], v[186:187], 0, s[20:21]
	s_add_i32 m0, s1, 0x2000
	s_nop 0
	global_load_lds_dwordx4 v[174:175], off
	s_barrier
	s_waitcnt lgkmcnt(0)
	s_setprio 1
	s_waitcnt lgkmcnt(0)
	v_mfma_f32_16x16x32_bf16 v[112:115], v[218:221], v[158:161], v[112:115]
	v_mfma_f32_16x16x32_bf16 v[104:107], v[226:229], v[158:161], v[104:107]
	v_mfma_f32_16x16x32_bf16 v[96:99], v[218:221], v[166:169], v[96:99]
	v_mfma_f32_16x16x32_bf16 v[88:91], v[226:229], v[166:169], v[88:91]
	v_mfma_f32_16x16x32_bf16 v[80:83], v[218:221], v[182:185], v[80:83]
	v_mfma_f32_16x16x32_bf16 v[72:75], v[226:229], v[182:185], v[72:75]
	v_mfma_f32_16x16x32_bf16 v[68:71], v[218:221], v[210:213], v[68:71]
	v_mfma_f32_16x16x32_bf16 v[64:67], v[226:229], v[210:213], v[64:67]
	v_mfma_f32_16x16x32_bf16 v[112:115], v[222:225], v[162:165], v[112:115]
	v_mfma_f32_16x16x32_bf16 v[104:107], v[230:233], v[162:165], v[104:107]
	v_mfma_f32_16x16x32_bf16 v[96:99], v[222:225], v[170:173], v[96:99]
	v_mfma_f32_16x16x32_bf16 v[88:91], v[230:233], v[170:173], v[88:91]
	v_mfma_f32_16x16x32_bf16 v[80:83], v[222:225], v[206:209], v[80:83]
	v_mfma_f32_16x16x32_bf16 v[72:75], v[230:233], v[206:209], v[72:75]
	v_mfma_f32_16x16x32_bf16 v[68:71], v[222:225], v[214:217], v[68:71]
	v_mfma_f32_16x16x32_bf16 v[64:67], v[230:233], v[214:217], v[64:67]
	s_setprio 0
	s_mov_b32 m0, s76
	v_lshl_add_u64 v[174:175], v[200:201], 0, s[20:21]
	s_barrier
	ds_read_b128 v[158:161], v145 offset:49152
	ds_read_b128 v[162:165], v145 offset:50176
	ds_read_b128 v[166:169], v145 offset:51200
	ds_read_b128 v[170:173], v145 offset:52224
	ds_read_b128 v[182:185], v145 offset:53248
	ds_read_b128 v[206:209], v145 offset:54272
	ds_read_b128 v[210:213], v145 offset:55296
	ds_read_b128 v[214:217], v145 offset:56320
	global_load_lds_dwordx4 v[174:175], off
	v_lshl_add_u64 v[174:175], v[202:203], 0, s[20:21]
	s_mov_b32 m0, s77
	s_nop 0
	global_load_lds_dwordx4 v[174:175], off
	s_barrier
	s_waitcnt lgkmcnt(0)
	s_setprio 1
	s_waitcnt lgkmcnt(0)
	v_mfma_f32_16x16x32_bf16 v[60:63], v[138:141], v[158:161], v[60:63]
	v_mfma_f32_16x16x32_bf16 v[56:59], v[150:153], v[158:161], v[56:59]
	v_mfma_f32_16x16x32_bf16 v[52:55], v[138:141], v[166:169], v[52:55]
	v_mfma_f32_16x16x32_bf16 v[44:47], v[150:153], v[166:169], v[44:47]
	v_mfma_f32_16x16x32_bf16 v[36:39], v[138:141], v[182:185], v[36:39]
	v_mfma_f32_16x16x32_bf16 v[28:31], v[150:153], v[182:185], v[28:31]
	v_mfma_f32_16x16x32_bf16 v[20:23], v[138:141], v[210:213], v[20:23]
	v_mfma_f32_16x16x32_bf16 v[12:15], v[150:153], v[210:213], v[12:15]
	v_mfma_f32_16x16x32_bf16 v[60:63], v[146:149], v[162:165], v[60:63]
	v_mfma_f32_16x16x32_bf16 v[56:59], v[154:157], v[162:165], v[56:59]
	v_mfma_f32_16x16x32_bf16 v[52:55], v[146:149], v[170:173], v[52:55]
	v_mfma_f32_16x16x32_bf16 v[44:47], v[154:157], v[170:173], v[44:47]
	v_mfma_f32_16x16x32_bf16 v[36:39], v[146:149], v[206:209], v[36:39]
	v_mfma_f32_16x16x32_bf16 v[28:31], v[154:157], v[206:209], v[28:31]
	v_mfma_f32_16x16x32_bf16 v[20:23], v[146:149], v[214:217], v[20:23]
	v_mfma_f32_16x16x32_bf16 v[12:15], v[154:157], v[214:217], v[12:15]
	s_setprio 0
	s_barrier
	s_add_u32 s2, s70, 0x80080
	s_addc_u32 s3, s71, 0
	s_add_i32 s1, s12, s53
	v_lshl_add_u64 v[138:139], s[2:3], 0, v[176:177]
	s_mov_b32 m0, s1
	s_nop 0
	global_load_lds_dwordx4 v[138:139], off
	v_lshl_add_u64 v[138:139], s[2:3], 0, v[128:129]
	s_add_i32 m0, s1, 0x2000
	s_nop 0
	global_load_lds_dwordx4 v[138:139], off
	s_waitcnt vmcnt(6)
	s_barrier
	s_setprio 1
	v_mfma_f32_16x16x32_bf16 v[48:51], v[218:221], v[158:161], v[48:51]
	v_mfma_f32_16x16x32_bf16 v[40:43], v[226:229], v[158:161], v[40:43]
	v_mfma_f32_16x16x32_bf16 v[32:35], v[218:221], v[166:169], v[32:35]
	v_mfma_f32_16x16x32_bf16 v[24:27], v[226:229], v[166:169], v[24:27]
	v_mfma_f32_16x16x32_bf16 v[16:19], v[218:221], v[182:185], v[16:19]
	v_mfma_f32_16x16x32_bf16 v[8:11], v[226:229], v[182:185], v[8:11]
	v_mfma_f32_16x16x32_bf16 v[4:7], v[218:221], v[210:213], v[4:7]
	v_mfma_f32_16x16x32_bf16 v[0:3], v[226:229], v[210:213], v[0:3]
	v_mfma_f32_16x16x32_bf16 v[48:51], v[222:225], v[162:165], v[48:51]
	v_mfma_f32_16x16x32_bf16 v[40:43], v[230:233], v[162:165], v[40:43]
	v_mfma_f32_16x16x32_bf16 v[32:35], v[222:225], v[170:173], v[32:35]
	v_mfma_f32_16x16x32_bf16 v[24:27], v[230:233], v[170:173], v[24:27]
	v_mfma_f32_16x16x32_bf16 v[16:19], v[222:225], v[206:209], v[16:19]
	v_mfma_f32_16x16x32_bf16 v[8:11], v[230:233], v[206:209], v[8:11]
	v_mfma_f32_16x16x32_bf16 v[4:7], v[222:225], v[214:217], v[4:7]
	v_mfma_f32_16x16x32_bf16 v[0:3], v[230:233], v[214:217], v[0:3]
	s_setprio 0
	s_add_i32 s87, s87, 2
	s_add_u32 s68, s68, 0x100
	s_addc_u32 s69, s69, 0
	s_add_u32 s83, s83, 0x100
	s_addc_u32 s86, s86, 0
	s_cmp_gt_u32 s87, 29
	s_barrier
	s_cbranch_scc0 .LBB0_189
	v_readlane_b32 s2, v253, 5
	v_lshl_or_b32 v140, s79, 8, v144
	v_readlane_b32 s3, v253, 6
	v_lshl_add_u32 v148, s80, 8, v142
	v_ashrrev_i32_e32 v141, 31, v140
	v_mov_b64_e32 v[138:139], s[2:3]
	v_mad_i64_i32 v[146:147], s[2:3], v148, s84, v[138:139]
	v_lshlrev_b64 v[140:141], 1, v[140:141]
	v_lshl_add_u64 v[146:147], v[146:147], 0, v[140:141]
	v_cvt_pk_bf16_f32 v124, v124, v125
	v_cvt_pk_bf16_f32 v125, v126, v127
	v_cvt_pk_bf16_f32 v126, v120, v121
	v_cvt_pk_bf16_f32 v127, v122, v123
	global_store_dwordx4 v[146:147], v[124:127], off sc1
	v_cvt_pk_bf16_f32 v112, v112, v113
	v_cvt_pk_bf16_f32 v113, v114, v115
	v_cvt_pk_bf16_f32 v114, v104, v105
	v_or_b32_e32 v104, 16, v148
	v_mad_i64_i32 v[104:105], s[2:3], v104, s84, v[138:139]
	v_cvt_pk_bf16_f32 v115, v106, v107
	global_store_dwordx4 v[146:147], v[112:115], off offset:256 sc1
	s_and_b64 vcc, exec, s[38:39]
	s_mov_b32 s79, s40
	v_lshl_add_u64 v[112:113], v[104:105], 0, v[140:141]
	v_cvt_pk_bf16_f32 v104, v116, v117
	v_cvt_pk_bf16_f32 v105, v118, v119
	v_cvt_pk_bf16_f32 v106, v108, v109
	v_cvt_pk_bf16_f32 v107, v110, v111
	global_store_dwordx4 v[112:113], v[104:107], off sc1
	v_cvt_pk_bf16_f32 v96, v96, v97
	v_cvt_pk_bf16_f32 v97, v98, v99
	v_cvt_pk_bf16_f32 v98, v88, v89
	v_or_b32_e32 v88, 32, v148
	v_mad_i64_i32 v[88:89], s[2:3], v88, s84, v[138:139]
	v_cvt_pk_bf16_f32 v99, v90, v91
	global_store_dwordx4 v[112:113], v[96:99], off offset:256 sc1
	s_mov_b32 s80, s42
	s_mov_b64 s[70:71], s[46:47]
	v_lshl_add_u64 v[96:97], v[88:89], 0, v[140:141]
	v_cvt_pk_bf16_f32 v88, v100, v101
	v_cvt_pk_bf16_f32 v89, v102, v103
	v_cvt_pk_bf16_f32 v90, v92, v93
	v_cvt_pk_bf16_f32 v91, v94, v95
	global_store_dwordx4 v[96:97], v[88:91], off sc1
	v_cvt_pk_bf16_f32 v80, v80, v81
	v_cvt_pk_bf16_f32 v81, v82, v83
	v_cvt_pk_bf16_f32 v82, v72, v73
	v_or_b32_e32 v72, 48, v148
	v_mad_i64_i32 v[72:73], s[2:3], v72, s84, v[138:139]
	v_cvt_pk_bf16_f32 v83, v74, v75
	global_store_dwordx4 v[96:97], v[80:83], off offset:256 sc1
	s_mov_b64 s[68:69], s[44:45]
	s_nop 0
	v_lshl_add_u64 v[80:81], v[72:73], 0, v[140:141]
	v_cvt_pk_bf16_f32 v72, v84, v85
	v_cvt_pk_bf16_f32 v73, v86, v87
	v_cvt_pk_bf16_f32 v74, v76, v77
	v_cvt_pk_bf16_f32 v75, v78, v79
	global_store_dwordx4 v[80:81], v[72:75], off sc1
	v_cvt_pk_bf16_f32 v68, v68, v69
	v_cvt_pk_bf16_f32 v69, v70, v71
	v_cvt_pk_bf16_f32 v70, v64, v65
	v_add_u32_e32 v64, 0x80, v148
	v_mad_i64_i32 v[64:65], s[2:3], v64, s84, v[138:139]
	v_lshl_add_u64 v[64:65], v[64:65], 0, v[140:141]
	v_cvt_pk_bf16_f32 v71, v66, v67
	global_store_dwordx4 v[80:81], v[68:71], off offset:256 sc1
	v_cvt_pk_bf16_f32 v60, v60, v61
	v_cvt_pk_bf16_f32 v61, v62, v63
	v_cvt_pk_bf16_f32 v62, v56, v57
	v_cvt_pk_bf16_f32 v63, v58, v59
	global_store_dwordx4 v[64:65], v[60:63], off sc1
	v_cvt_pk_bf16_f32 v48, v48, v49
	v_cvt_pk_bf16_f32 v49, v50, v51
	v_cvt_pk_bf16_f32 v50, v40, v41
	v_add_u32_e32 v40, 0x90, v148
	v_mad_i64_i32 v[40:41], s[2:3], v40, s84, v[138:139]
	v_cvt_pk_bf16_f32 v51, v42, v43
	global_store_dwordx4 v[64:65], v[48:51], off offset:256 sc1
	s_nop 1
	v_lshl_add_u64 v[48:49], v[40:41], 0, v[140:141]
	v_cvt_pk_bf16_f32 v40, v52, v53
	v_cvt_pk_bf16_f32 v41, v54, v55
	v_cvt_pk_bf16_f32 v42, v44, v45
	v_cvt_pk_bf16_f32 v43, v46, v47
	global_store_dwordx4 v[48:49], v[40:43], off sc1
	v_cvt_pk_bf16_f32 v32, v32, v33
	v_cvt_pk_bf16_f32 v33, v34, v35
	v_cvt_pk_bf16_f32 v34, v24, v25
	v_add_u32_e32 v24, 0xa0, v148
	v_mad_i64_i32 v[24:25], s[2:3], v24, s84, v[138:139]
	v_cvt_pk_bf16_f32 v35, v26, v27
	global_store_dwordx4 v[48:49], v[32:35], off offset:256 sc1
	s_nop 1
	v_lshl_add_u64 v[32:33], v[24:25], 0, v[140:141]
	v_cvt_pk_bf16_f32 v24, v36, v37
	v_cvt_pk_bf16_f32 v25, v38, v39
	v_cvt_pk_bf16_f32 v26, v28, v29
	v_cvt_pk_bf16_f32 v27, v30, v31
	global_store_dwordx4 v[32:33], v[24:27], off sc1
	v_cvt_pk_bf16_f32 v16, v16, v17
	v_cvt_pk_bf16_f32 v17, v18, v19
	v_cvt_pk_bf16_f32 v18, v8, v9
	v_add_u32_e32 v8, 0xb0, v148
	v_mad_i64_i32 v[8:9], s[2:3], v8, s84, v[138:139]
	v_cvt_pk_bf16_f32 v19, v10, v11
	global_store_dwordx4 v[32:33], v[16:19], off offset:256 sc1
	s_nop 1
	v_lshl_add_u64 v[16:17], v[8:9], 0, v[140:141]
	v_cvt_pk_bf16_f32 v8, v20, v21
	v_cvt_pk_bf16_f32 v9, v22, v23
	v_cvt_pk_bf16_f32 v10, v12, v13
	v_cvt_pk_bf16_f32 v11, v14, v15
	global_store_dwordx4 v[16:17], v[8:11], off sc1
	v_cvt_pk_bf16_f32 v4, v4, v5
	v_cvt_pk_bf16_f32 v5, v6, v7
	v_cvt_pk_bf16_f32 v6, v0, v1
	v_cvt_pk_bf16_f32 v7, v2, v3
	global_store_dwordx4 v[16:17], v[4:7], off offset:256 sc1
	s_cbranch_vccz .LBB0_186
	s_waitcnt vmcnt(0)
	s_cmpk_gt_u32 s34, 0xff
	s_cbranch_scc1 .LBB0_193
	s_barrier
